# spatial-gating phase: nontemporal hint on the read-once u and v tile loads
# baseline (speedup 1.0000x reference)
.LBB0_688:
	s_and_b32 s33, s3, 0xffffff80
	v_mov_b32_e32 v71, v61
	v_mov_b32_e32 v73, v61
	v_mov_b32_e32 v75, v61
	v_mov_b32_e32 v77, v61
	v_or_b32_e32 v252, s33, v80
	v_ashrrev_i32_e32 v253, 31, v252
	v_lshl_add_u64 v[252:253], v[252:253], 2, s[4:5]
	global_load_dwordx4 v[0:3], v[252:253], off
	s_and_b32 s98, s87, 7
	s_lshl_b32 s99, s98, 14
	v_mov_b32_e32 v217, 0
	v_or_b32_e32 v216, s99, v83
	v_lshlrev_b32_e32 v216, 2, v216
	v_lshl_add_u64 v[252:253], v[62:63], 0, v[216:217]
	global_load_dwordx4 v[8:11], v[252:253], off
	v_or_b32_e32 v216, s99, v84
	v_lshlrev_b32_e32 v216, 2, v216
	v_lshl_add_u64 v[252:253], v[62:63], 0, v[216:217]
	global_load_dwordx4 v[12:15], v[252:253], off
	v_or_b32_e32 v216, s99, v85
	v_lshlrev_b32_e32 v216, 2, v216
	v_lshl_add_u64 v[252:253], v[62:63], 0, v[216:217]
	global_load_dwordx4 v[16:19], v[252:253], off
	v_or_b32_e32 v216, s99, v86
	v_lshlrev_b32_e32 v216, 2, v216
	v_lshl_add_u64 v[252:253], v[62:63], 0, v[216:217]
	global_load_dwordx4 v[20:23], v[252:253], off
	v_or_b32_e32 v216, s99, v87
	v_lshlrev_b32_e32 v216, 2, v216
	v_lshl_add_u64 v[252:253], v[62:63], 0, v[216:217]
	global_load_dwordx4 v[24:27], v[252:253], off
	v_or_b32_e32 v216, s99, v88
	v_lshlrev_b32_e32 v216, 2, v216
	v_lshl_add_u64 v[252:253], v[62:63], 0, v[216:217]
	global_load_dwordx4 v[28:31], v[252:253], off
	v_or_b32_e32 v216, s99, v89
	v_lshlrev_b32_e32 v216, 2, v216
	v_lshl_add_u64 v[252:253], v[62:63], 0, v[216:217]
	global_load_dwordx4 v[32:35], v[252:253], off
	v_add_lshl_u32 v216, s99, v90, 2
	v_lshl_add_u64 v[252:253], v[62:63], 0, v[216:217]
	global_load_dwordx4 v[36:39], v[252:253], off
	v_or_b32_e32 v252, s33, v81
	v_ashrrev_i32_e32 v253, 31, v252
	v_lshlrev_b64 v[252:253], 13, v[252:253]
	v_lshl_add_u64 v[252:253], s[96:97], 0, v[252:253]
	s_lshl_b32 s100, s98, 9
	s_mov_b32 s101, 0
	v_lshl_add_u64 v[252:253], v[252:253], 0, s[100:101]
	s_add_u32 s100, s96, s100
	s_addc_u32 s101, s97, 0
	s_mov_b64 s[98:99], 0x1000
	v_lshl_add_u64 v[252:253], v[252:253], 0, s[98:99]
	v_lshl_add_u64 v[216:217], v[252:253], 0, v[66:67]
	global_load_dwordx4 v[40:43], v[216:217], off nt
	v_lshl_add_u64 v[214:215], v[252:253], 0, v[68:69]
	global_load_dwordx4 v[44:47], v[214:215], off nt
	global_load_dwordx4 v[48:51], v[216:217], off offset:128 nt
	v_lshl_add_u64 v[214:215], v[252:253], 0, v[70:71]
	global_load_dwordx4 v[52:55], v[214:215], off nt
	global_load_dwordx4 v[56:59], v[216:217], off offset:256 nt
	v_lshl_add_u64 v[214:215], v[252:253], 0, v[72:73]
	global_load_dwordx4 v[164:167], v[214:215], off nt
	global_load_dwordx4 v[168:171], v[216:217], off offset:384 nt
	v_lshl_add_u64 v[214:215], v[252:253], 0, v[74:75]
	global_load_dwordx4 v[172:175], v[214:215], off nt
	s_and_b32 s98, s87, 7
	s_lshl_b32 s99, s98, 7
	v_add_lshl_u32 v231, s99, v82, 2
	global_load_dword v234, v231, s[74:75]
	global_load_dword v235, v231, s[74:75] offset:64
	global_load_dword v237, v231, s[74:75] offset:128
	global_load_dword v228, v231, s[74:75] offset:192
	v_add_u32_e32 v252, s33, v82
	v_ashrrev_i32_e32 v253, 31, v252
	v_lshlrev_b64 v[252:253], 13, v[252:253]
	v_lshl_add_u64 v[252:253], s[100:101], 0, v[252:253]
	v_lshl_add_u64 v[252:253], v[252:253], 0, v[76:77]
	global_load_dwordx2 v[184:185], v[252:253], off nt
	global_load_dwordx2 v[186:187], v[252:253], off offset:32 nt
	global_load_dwordx2 v[188:189], v[252:253], off offset:64 nt
	global_load_dwordx2 v[190:191], v[252:253], off offset:96 nt
	v_add_u32_e32 v252, s33, v99
	v_ashrrev_i32_e32 v253, 31, v252
	v_lshlrev_b64 v[252:253], 13, v[252:253]
	v_lshl_add_u64 v[252:253], s[100:101], 0, v[252:253]
	v_lshl_add_u64 v[252:253], v[252:253], 0, v[76:77]
	global_load_dwordx2 v[192:193], v[252:253], off nt
	global_load_dwordx2 v[194:195], v[252:253], off offset:32 nt
	global_load_dwordx2 v[196:197], v[252:253], off offset:64 nt
	global_load_dwordx2 v[198:199], v[252:253], off offset:96 nt
	v_add_u32_e32 v252, s33, v100
	v_ashrrev_i32_e32 v253, 31, v252
	v_lshlrev_b64 v[252:253], 13, v[252:253]
	v_lshl_add_u64 v[252:253], s[100:101], 0, v[252:253]
	v_lshl_add_u64 v[252:253], v[252:253], 0, v[76:77]
	global_load_dwordx2 v[200:201], v[252:253], off nt
	global_load_dwordx2 v[202:203], v[252:253], off offset:32 nt
	global_load_dwordx2 v[204:205], v[252:253], off offset:64 nt
	global_load_dwordx2 v[206:207], v[252:253], off offset:96 nt
	v_add_u32_e32 v252, s33, v101
	v_ashrrev_i32_e32 v253, 31, v252
	v_lshlrev_b64 v[252:253], 13, v[252:253]
	v_lshl_add_u64 v[252:253], s[100:101], 0, v[252:253]
	v_lshl_add_u64 v[252:253], v[252:253], 0, v[76:77]
	global_load_dwordx2 v[208:209], v[252:253], off nt
	global_load_dwordx2 v[210:211], v[252:253], off offset:32 nt
	global_load_dwordx2 v[212:213], v[252:253], off offset:64 nt
	global_load_dwordx2 v[214:215], v[252:253], off offset:96 nt
	s_lshl_b32 s98, s98, 10
	s_mov_b32 s99, 0
	v_lshl_add_u64 v[252:253], v[64:65], 0, s[98:99]
	global_load_dwordx4 v[240:243], v[252:253], off
	global_load_dwordx4 v[244:247], v[252:253], off offset:64
	global_load_dwordx4 v[248:251], v[252:253], off offset:128
	global_load_dwordx2 v[216:217], v[252:253], off offset:192
	global_load_dwordx2 v[252:253], v[252:253], off offset:200
	s_and_b32 s76, s87, 7
	s_lshl_b32 s0, s76, 14
	s_lshl_b32 s72, s76, 9
	v_mov_b32_e32 v71, v61
	v_mov_b32_e32 v73, v61
	v_mov_b32_e32 v75, v61
	s_lshl_b32 s79, s76, 7
	v_mov_b32_e32 v77, v61
	s_waitcnt vmcnt(41)
	v_fmamk_f32 v0, v0, 0x3a000000, v102
	v_rsq_f32_e32 v4, v0
	v_fmamk_f32 v0, v1, 0x3a000000, v102
	v_rsq_f32_e32 v5, v0
	v_fmamk_f32 v0, v2, 0x3a000000, v102
	v_rsq_f32_e32 v6, v0
	v_fmamk_f32 v0, v3, 0x3a000000, v102
	v_rsq_f32_e32 v7, v0
	v_or_b32_e32 v0, s0, v83
	v_lshlrev_b32_e32 v60, 2, v0
	v_lshl_add_u64 v[0:1], v[62:63], 0, v[60:61]
	s_waitcnt vmcnt(40)
	v_mov_b32_e32 v0, v8
	v_mov_b32_e32 v1, v9
	v_mov_b32_e32 v2, v10
	v_mov_b32_e32 v3, v11
	v_mul_f32_e32 v0, v4, v0
	v_cndmask_b32_e64 v0, v0, 0, vcc
	v_mul_f32_e32 v1, v5, v1
	v_cndmask_b32_e64 v1, 0, v1, s[6:7]
	v_mul_f32_e32 v2, v2, v6
	v_mul_f32_e32 v3, v3, v7
	v_cvt_pk_bf16_f32 v0, v0, v1
	v_cndmask_b32_e64 v2, v2, 0, s[8:9]
	v_cndmask_b32_e64 v3, v3, 0, s[10:11]
	v_cvt_pk_bf16_f32 v1, v2, v3
	ds_write_b64 v103, v[0:1]
	v_or_b32_e32 v0, s0, v84
	v_lshlrev_b32_e32 v60, 2, v0
	v_lshl_add_u64 v[0:1], v[62:63], 0, v[60:61]
	s_waitcnt vmcnt(39)
	v_mov_b32_e32 v0, v12
	v_mov_b32_e32 v1, v13
	v_mov_b32_e32 v2, v14
	v_mov_b32_e32 v3, v15
	v_mul_f32_e32 v0, v4, v0
	v_cndmask_b32_e64 v0, v0, 0, s[12:13]
	v_mul_f32_e32 v1, v5, v1
	v_cndmask_b32_e64 v1, 0, v1, s[14:15]
	v_mul_f32_e32 v2, v6, v2
	v_mul_f32_e32 v3, v7, v3
	v_cvt_pk_bf16_f32 v0, v0, v1
	v_cndmask_b32_e64 v2, v2, 0, s[16:17]
	v_cndmask_b32_e64 v3, v3, 0, s[18:19]
	v_cvt_pk_bf16_f32 v1, v2, v3
	ds_write_b64 v103, v[0:1] offset:4352
	v_or_b32_e32 v0, s0, v85
	v_lshlrev_b32_e32 v60, 2, v0
	v_lshl_add_u64 v[0:1], v[62:63], 0, v[60:61]
	s_waitcnt vmcnt(38)
	v_mov_b32_e32 v0, v16
	v_mov_b32_e32 v1, v17
	v_mov_b32_e32 v2, v18
	v_mov_b32_e32 v3, v19
	v_mul_f32_e32 v0, v4, v0
	v_cndmask_b32_e64 v0, v0, 0, s[20:21]
	v_mul_f32_e32 v1, v5, v1
	v_cndmask_b32_e64 v1, 0, v1, s[22:23]
	v_mul_f32_e32 v2, v6, v2
	v_mul_f32_e32 v3, v7, v3
	v_cvt_pk_bf16_f32 v0, v0, v1
	v_cndmask_b32_e64 v2, v2, 0, s[24:25]
	v_cndmask_b32_e64 v3, v3, 0, s[26:27]
	v_cvt_pk_bf16_f32 v1, v2, v3
	ds_write_b64 v103, v[0:1] offset:8704
	v_or_b32_e32 v0, s0, v86
	v_lshlrev_b32_e32 v60, 2, v0
	v_lshl_add_u64 v[0:1], v[62:63], 0, v[60:61]
	s_waitcnt vmcnt(37)
	v_mov_b32_e32 v0, v20
	v_mov_b32_e32 v1, v21
	v_mov_b32_e32 v2, v22
	v_mov_b32_e32 v3, v23
	v_mul_f32_e32 v0, v4, v0
	v_cndmask_b32_e64 v0, v0, 0, s[28:29]
	v_mul_f32_e32 v1, v5, v1
	v_cndmask_b32_e64 v1, 0, v1, s[30:31]
	v_mul_f32_e32 v2, v6, v2
	v_mul_f32_e32 v3, v7, v3
	v_cvt_pk_bf16_f32 v0, v0, v1
	v_cndmask_b32_e64 v2, v2, 0, s[34:35]
	v_cndmask_b32_e64 v3, v3, 0, s[36:37]
	v_cvt_pk_bf16_f32 v1, v2, v3
	ds_write_b64 v103, v[0:1] offset:13056
	v_or_b32_e32 v0, s0, v87
	v_lshlrev_b32_e32 v60, 2, v0
	v_lshl_add_u64 v[0:1], v[62:63], 0, v[60:61]
	s_waitcnt vmcnt(36)
	v_mov_b32_e32 v0, v24
	v_mov_b32_e32 v1, v25
	v_mov_b32_e32 v2, v26
	v_mov_b32_e32 v3, v27
	v_mul_f32_e32 v0, v4, v0
	v_cndmask_b32_e64 v0, v0, 0, s[38:39]
	v_mul_f32_e32 v1, v5, v1
	v_cndmask_b32_e64 v1, 0, v1, s[40:41]
	v_mul_f32_e32 v2, v6, v2
	v_mul_f32_e32 v3, v7, v3
	v_cvt_pk_bf16_f32 v0, v0, v1
	v_cndmask_b32_e64 v2, v2, 0, s[42:43]
	v_cndmask_b32_e64 v3, v3, 0, s[44:45]
	v_cvt_pk_bf16_f32 v1, v2, v3
	ds_write_b64 v103, v[0:1] offset:17408
	v_or_b32_e32 v0, s0, v88
	v_lshlrev_b32_e32 v60, 2, v0
	v_lshl_add_u64 v[0:1], v[62:63], 0, v[60:61]
	s_waitcnt vmcnt(35)
	v_mov_b32_e32 v0, v28
	v_mov_b32_e32 v1, v29
	v_mov_b32_e32 v2, v30
	v_mov_b32_e32 v3, v31
	v_mul_f32_e32 v0, v4, v0
	v_cndmask_b32_e64 v0, v0, 0, s[46:47]
	v_mul_f32_e32 v1, v5, v1
	v_cndmask_b32_e64 v1, 0, v1, s[48:49]
	v_mul_f32_e32 v2, v6, v2
	v_mul_f32_e32 v3, v7, v3
	v_cvt_pk_bf16_f32 v0, v0, v1
	v_cndmask_b32_e64 v2, v2, 0, s[50:51]
	v_cndmask_b32_e64 v3, v3, 0, s[52:53]
	v_cvt_pk_bf16_f32 v1, v2, v3
	ds_write_b64 v103, v[0:1] offset:21760
	v_or_b32_e32 v0, s0, v89
	v_lshlrev_b32_e32 v60, 2, v0
	v_lshl_add_u64 v[0:1], v[62:63], 0, v[60:61]
	v_add_lshl_u32 v60, s0, v90, 2
	s_mov_b64 s[0:1], 0x1000
	s_waitcnt vmcnt(34)
	v_mov_b32_e32 v0, v32
	v_mov_b32_e32 v1, v33
	v_mov_b32_e32 v2, v34
	v_mov_b32_e32 v3, v35
	v_mul_f32_e32 v0, v4, v0
	v_mul_f32_e32 v1, v5, v1
	v_cndmask_b32_e64 v0, v0, 0, s[54:55]
	v_cndmask_b32_e64 v1, 0, v1, s[56:57]
	v_mul_f32_e32 v2, v6, v2
	v_mul_f32_e32 v3, v7, v3
	v_cndmask_b32_e64 v2, v2, 0, s[58:59]
	v_cndmask_b32_e64 v3, v3, 0, s[60:61]
	v_cvt_pk_bf16_f32 v0, v0, v1
	v_cvt_pk_bf16_f32 v1, v2, v3
	ds_write_b64 v103, v[0:1] offset:26112
	v_lshl_add_u64 v[0:1], v[62:63], 0, v[60:61]
	v_add_lshl_u32 v60, s79, v82, 2
	s_waitcnt vmcnt(33)
	v_mov_b32_e32 v0, v36
	v_mov_b32_e32 v1, v37
	v_mov_b32_e32 v2, v38
	v_mov_b32_e32 v3, v39
	v_mul_f32_e32 v0, v4, v0
	v_cndmask_b32_e64 v0, v0, 0, s[62:63]
	v_mul_f32_e32 v1, v5, v1
	v_cndmask_b32_e64 v1, 0, v1, s[64:65]
	v_mul_f32_e32 v2, v6, v2
	v_mul_f32_e32 v3, v7, v3
	v_cvt_pk_bf16_f32 v0, v0, v1
	v_cndmask_b32_e64 v2, v2, 0, s[66:67]
	v_cndmask_b32_e64 v3, v3, 0, s[68:69]
	v_cvt_pk_bf16_f32 v1, v2, v3
	ds_write_b64 v103, v[0:1] offset:30464
	v_or_b32_e32 v0, s33, v81
	v_ashrrev_i32_e32 v1, 31, v0
	v_lshlrev_b64 v[0:1], 13, v[0:1]
	v_lshl_add_u64 v[0:1], s[96:97], 0, v[0:1]
	v_lshl_add_u64 v[0:1], v[0:1], 0, s[72:73]
	v_lshl_add_u64 v[0:1], v[0:1], 0, s[0:1]
	v_lshl_add_u64 v[2:3], v[0:1], 0, v[66:67]
	s_add_u32 s0, s96, s72
	s_addc_u32 s1, s97, 0
	s_lshl_b32 s72, s76, 10
	v_lshl_add_u64 v[78:79], v[64:65], 0, s[72:73]
	s_add_i32 s87, s87, s94
	s_add_i32 s3, s3, s86
	s_cmpk_lt_i32 s87, 0x400
	s_waitcnt vmcnt(32)
	v_mov_b32_e32 v4, v40
	v_mov_b32_e32 v5, v41
	v_mov_b32_e32 v6, v42
	v_mov_b32_e32 v7, v43
	ds_write_b16 v91, v4 offset:34816
	ds_write_b16_d16_hi v91, v4 offset:35088
	ds_write_b16 v91, v5 offset:35360
	ds_write_b16_d16_hi v91, v5 offset:35632
	ds_write_b16 v91, v6 offset:35904
	ds_write_b16_d16_hi v91, v6 offset:36176
	ds_write_b16 v91, v7 offset:36448
	ds_write_b16_d16_hi v91, v7 offset:36720
	v_lshl_add_u64 v[4:5], v[0:1], 0, v[68:69]
	s_waitcnt vmcnt(31)
	v_mov_b32_e32 v4, v44
	v_mov_b32_e32 v5, v45
	v_mov_b32_e32 v6, v46
	v_mov_b32_e32 v7, v47
	ds_write_b16 v92, v4 offset:34816
	ds_write_b16_d16_hi v92, v4 offset:35088
	ds_write_b16 v92, v5 offset:35360
	ds_write_b16_d16_hi v92, v5 offset:35632
	ds_write_b16 v92, v6 offset:35904
	ds_write_b16_d16_hi v92, v6 offset:36176
	ds_write_b16 v92, v7 offset:36448
	ds_write_b16_d16_hi v92, v7 offset:36720
	s_waitcnt vmcnt(30)
	v_mov_b32_e32 v4, v48
	v_mov_b32_e32 v5, v49
	v_mov_b32_e32 v6, v50
	v_mov_b32_e32 v7, v51
	ds_write_b16 v93, v4 offset:34816
	ds_write_b16_d16_hi v93, v4 offset:35088
	ds_write_b16 v91, v5 offset:52768
	ds_write_b16_d16_hi v91, v5 offset:53040
	ds_write_b16 v91, v6 offset:53312
	ds_write_b16_d16_hi v91, v6 offset:53584
	ds_write_b16 v91, v7 offset:53856
	ds_write_b16_d16_hi v91, v7 offset:54128
	v_lshl_add_u64 v[4:5], v[0:1], 0, v[70:71]
	s_waitcnt vmcnt(29)
	v_mov_b32_e32 v4, v52
	v_mov_b32_e32 v5, v53
	v_mov_b32_e32 v6, v54
	v_mov_b32_e32 v7, v55
	ds_write_b16 v94, v4 offset:34816
	ds_write_b16_d16_hi v94, v4 offset:35088
	ds_write_b16 v94, v5 offset:35360
	ds_write_b16_d16_hi v94, v5 offset:35632
	ds_write_b16 v94, v6 offset:35904
	ds_write_b16_d16_hi v94, v6 offset:36176
	ds_write_b16 v94, v7 offset:36448
	ds_write_b16_d16_hi v94, v7 offset:36720
	s_waitcnt vmcnt(28)
	v_mov_b32_e32 v4, v56
	v_mov_b32_e32 v5, v57
	v_mov_b32_e32 v6, v58
	v_mov_b32_e32 v7, v59
	ds_write_b16 v95, v4 offset:34816
	ds_write_b16_d16_hi v95, v4 offset:35088
	ds_write_b16 v95, v5 offset:35360
	ds_write_b16_d16_hi v95, v5 offset:35632
	ds_write_b16 v95, v6 offset:35904
	ds_write_b16_d16_hi v95, v6 offset:36176
	ds_write_b16 v95, v7 offset:36448
	ds_write_b16_d16_hi v95, v7 offset:36720
	v_lshl_add_u64 v[4:5], v[0:1], 0, v[72:73]
	v_lshl_add_u64 v[0:1], v[0:1], 0, v[74:75]
	s_waitcnt vmcnt(27)
	v_mov_b32_e32 v4, v164
	v_mov_b32_e32 v5, v165
	v_mov_b32_e32 v6, v166
	v_mov_b32_e32 v7, v167
	ds_write_b16 v96, v4 offset:34816
	ds_write_b16_d16_hi v96, v4 offset:35088
	ds_write_b16 v96, v5 offset:35360
	ds_write_b16_d16_hi v96, v5 offset:35632
	ds_write_b16 v96, v6 offset:35904
	ds_write_b16_d16_hi v96, v6 offset:36176
	ds_write_b16 v96, v7 offset:36448
	ds_write_b16_d16_hi v96, v7 offset:36720
	s_waitcnt vmcnt(26)
	v_mov_b32_e32 v2, v168
	v_mov_b32_e32 v3, v169
	v_mov_b32_e32 v4, v170
	v_mov_b32_e32 v5, v171
	ds_write_b16 v97, v2 offset:34816
	ds_write_b16_d16_hi v97, v2 offset:35088
	ds_write_b16 v95, v3 offset:52768
	ds_write_b16_d16_hi v95, v3 offset:53040
	ds_write_b16 v95, v4 offset:53312
	ds_write_b16_d16_hi v95, v4 offset:53584
	ds_write_b16 v95, v5 offset:53856
	ds_write_b16_d16_hi v95, v5 offset:54128
	s_waitcnt vmcnt(25)
	v_mov_b32_e32 v0, v172
	v_mov_b32_e32 v1, v173
	v_mov_b32_e32 v2, v174
	v_mov_b32_e32 v3, v175
	ds_write_b16 v98, v0 offset:34816
	ds_write_b16_d16_hi v98, v0 offset:35088
	ds_write_b16 v98, v1 offset:35360
	ds_write_b16_d16_hi v98, v1 offset:35632
	ds_write_b16 v98, v2 offset:35904
	ds_write_b16_d16_hi v98, v2 offset:36176
	ds_write_b16 v98, v3 offset:36448
	ds_write_b16_d16_hi v98, v3 offset:36720
	s_waitcnt lgkmcnt(0)
	s_barrier
	ds_read_b128 v[0:3], v104
	ds_read_b128 v[4:7], v104 offset:4352
	ds_read_b128 v[8:11], v104 offset:8704
	ds_read_b128 v[12:15], v104 offset:13056
	ds_read_b128 v[16:19], v105 offset:34816
	ds_read_b128 v[20:23], v105 offset:39168
	ds_read_b128 v[24:27], v105 offset:43520
	ds_read_b128 v[28:31], v105 offset:47872
	s_waitcnt lgkmcnt(3)
	v_mfma_f32_16x16x32_bf16 v[32:35], v[16:19], v[0:3], 0
	s_waitcnt lgkmcnt(2)
	v_mfma_f32_16x16x32_bf16 v[36:39], v[20:23], v[0:3], 0
	s_waitcnt lgkmcnt(1)
	v_mfma_f32_16x16x32_bf16 v[40:43], v[24:27], v[0:3], 0
	s_waitcnt lgkmcnt(0)
	v_mfma_f32_16x16x32_bf16 v[0:3], v[28:31], v[0:3], 0
	v_mfma_f32_16x16x32_bf16 v[44:47], v[16:19], v[4:7], 0
	v_mfma_f32_16x16x32_bf16 v[48:51], v[20:23], v[4:7], 0
	v_mfma_f32_16x16x32_bf16 v[52:55], v[24:27], v[4:7], 0
	v_mfma_f32_16x16x32_bf16 v[4:7], v[28:31], v[4:7], 0
	v_mfma_f32_16x16x32_bf16 v[56:59], v[16:19], v[8:11], 0
	v_mfma_f32_16x16x32_bf16 v[106:109], v[20:23], v[8:11], 0
	v_mfma_f32_16x16x32_bf16 v[110:113], v[24:27], v[8:11], 0
	v_mfma_f32_16x16x32_bf16 v[8:11], v[28:31], v[8:11], 0
	v_mfma_f32_16x16x32_bf16 v[16:19], v[16:19], v[12:15], 0
	v_mfma_f32_16x16x32_bf16 v[20:23], v[20:23], v[12:15], 0
	v_mfma_f32_16x16x32_bf16 v[24:27], v[24:27], v[12:15], 0
	v_mfma_f32_16x16x32_bf16 v[12:15], v[28:31], v[12:15], 0
	ds_read_b128 v[28:31], v104 offset:64
	ds_read_b128 v[114:117], v104 offset:4416
	ds_read_b128 v[118:121], v104 offset:8768
	ds_read_b128 v[122:125], v104 offset:13120
	ds_read_b128 v[126:129], v105 offset:34880
	ds_read_b128 v[130:133], v105 offset:39232
	ds_read_b128 v[134:137], v105 offset:43584
	ds_read_b128 v[138:141], v105 offset:47936
	s_waitcnt lgkmcnt(3)
	v_mfma_f32_16x16x32_bf16 v[32:35], v[126:129], v[28:31], v[32:35]
	s_waitcnt lgkmcnt(2)
	v_mfma_f32_16x16x32_bf16 v[36:39], v[130:133], v[28:31], v[36:39]
	s_waitcnt lgkmcnt(1)
	v_mfma_f32_16x16x32_bf16 v[40:43], v[134:137], v[28:31], v[40:43]
	s_waitcnt lgkmcnt(0)
	v_mfma_f32_16x16x32_bf16 v[0:3], v[138:141], v[28:31], v[0:3]
	v_mfma_f32_16x16x32_bf16 v[28:31], v[126:129], v[114:117], v[44:47]
	v_mfma_f32_16x16x32_bf16 v[44:47], v[130:133], v[114:117], v[48:51]
	v_mfma_f32_16x16x32_bf16 v[48:51], v[134:137], v[114:117], v[52:55]
	v_mfma_f32_16x16x32_bf16 v[4:7], v[138:141], v[114:117], v[4:7]
	v_mfma_f32_16x16x32_bf16 v[52:55], v[126:129], v[118:121], v[56:59]
	v_mfma_f32_16x16x32_bf16 v[56:59], v[130:133], v[118:121], v[106:109]
	v_mfma_f32_16x16x32_bf16 v[106:109], v[134:137], v[118:121], v[110:113]
	v_mfma_f32_16x16x32_bf16 v[8:11], v[138:141], v[118:121], v[8:11]
	v_mfma_f32_16x16x32_bf16 v[16:19], v[126:129], v[122:125], v[16:19]
	v_mfma_f32_16x16x32_bf16 v[20:23], v[130:133], v[122:125], v[20:23]
	v_mfma_f32_16x16x32_bf16 v[24:27], v[134:137], v[122:125], v[24:27]
	v_mfma_f32_16x16x32_bf16 v[12:15], v[138:141], v[122:125], v[12:15]
	ds_read_b128 v[110:113], v104 offset:128
	ds_read_b128 v[114:117], v104 offset:4480
	ds_read_b128 v[118:121], v104 offset:8832
	ds_read_b128 v[122:125], v104 offset:13184
	ds_read_b128 v[126:129], v105 offset:34944
	ds_read_b128 v[130:133], v105 offset:39296
	ds_read_b128 v[134:137], v105 offset:43648
	ds_read_b128 v[138:141], v105 offset:48000
	s_waitcnt lgkmcnt(3)
	v_mfma_f32_16x16x32_bf16 v[32:35], v[126:129], v[110:113], v[32:35]
	s_waitcnt lgkmcnt(2)
	v_mfma_f32_16x16x32_bf16 v[36:39], v[130:133], v[110:113], v[36:39]
	s_waitcnt lgkmcnt(1)
	v_mfma_f32_16x16x32_bf16 v[40:43], v[134:137], v[110:113], v[40:43]
	s_waitcnt lgkmcnt(0)
	v_mfma_f32_16x16x32_bf16 v[0:3], v[138:141], v[110:113], v[0:3]
	v_mfma_f32_16x16x32_bf16 v[28:31], v[126:129], v[114:117], v[28:31]
	v_mfma_f32_16x16x32_bf16 v[110:113], v[130:133], v[114:117], v[44:47]
	v_mfma_f32_16x16x32_bf16 v[142:145], v[134:137], v[114:117], v[48:51]
	v_mfma_f32_16x16x32_bf16 v[4:7], v[138:141], v[114:117], v[4:7]
	v_mfma_f32_16x16x32_bf16 v[114:117], v[126:129], v[118:121], v[52:55]
	v_mfma_f32_16x16x32_bf16 v[146:149], v[130:133], v[118:121], v[56:59]
	v_mfma_f32_16x16x32_bf16 v[106:109], v[134:137], v[118:121], v[106:109]
	v_mfma_f32_16x16x32_bf16 v[8:11], v[138:141], v[118:121], v[8:11]
	v_mfma_f32_16x16x32_bf16 v[118:121], v[126:129], v[122:125], v[16:19]
	v_mfma_f32_16x16x32_bf16 v[126:129], v[130:133], v[122:125], v[20:23]
	v_mfma_f32_16x16x32_bf16 v[130:133], v[134:137], v[122:125], v[24:27]
	v_mfma_f32_16x16x32_bf16 v[122:125], v[138:141], v[122:125], v[12:15]
	s_nop 2
	ds_read_b128 v[12:15], v104 offset:192
	ds_read_b128 v[16:19], v104 offset:4544
	ds_read_b128 v[134:137], v104 offset:8896
	ds_read_b128 v[138:141], v104 offset:13248
	ds_read_b128 v[150:153], v105 offset:35008
	ds_read_b128 v[154:157], v105 offset:39360
	ds_read_b128 v[158:161], v105 offset:43712
	ds_read_b128 v[176:179], v105 offset:48064
	s_waitcnt lgkmcnt(1)
	v_mfma_f32_16x16x32_bf16 v[20:23], v[158:161], v[134:137], v[106:109]
	s_nop 2
	v_add_u32_e32 v106, s33, v82
	v_ashrrev_i32_e32 v107, 31, v106
	v_lshlrev_b64 v[106:107], 13, v[106:107]
	v_mfma_f32_16x16x32_bf16 v[52:55], v[158:161], v[12:15], v[40:43]
	v_mfma_f32_16x16x32_bf16 v[40:43], v[154:157], v[16:19], v[110:113]
	s_nop 2
	v_lshl_add_u64 v[110:111], s[0:1], 0, v[106:107]
	v_lshl_add_u64 v[110:111], v[110:111], 0, v[76:77]
	v_mfma_f32_16x16x32_bf16 v[180:183], v[150:153], v[12:15], v[32:35]
	s_waitcnt vmcnt(0)
	v_mov_b32_e32 v71, v234
	v_mov_b32_e32 v106, v240
	v_mov_b32_e32 v107, v241
	v_mov_b32_e32 v108, v242
	v_mov_b32_e32 v109, v243
	v_mov_b32_e32 v112, v184
	v_mov_b32_e32 v113, v185
	v_lshlrev_b32_e32 v73, 16, v112
	s_nop 5
	v_fma_f32 v75, v180, v106, v71
	v_mul_f32_e32 v73, v75, v73
	v_and_b32_e32 v75, 0xffff0000, v112
	v_fma_f32 v106, v181, v107, v71
	v_mul_f32_e32 v75, v106, v75
	v_lshlrev_b32_e32 v106, 16, v113
	v_fma_f32 v107, v182, v108, v71
	v_mul_f32_e32 v107, v107, v106
	v_and_b32_e32 v106, 0xffff0000, v113
	v_fma_f32 v108, v183, v109, v71
	v_mul_f32_e32 v108, v108, v106
	v_cvt_pk_bf16_f32 v106, v73, v75
	v_cvt_pk_bf16_f32 v107, v107, v108
	global_store_dwordx2 v[110:111], v[106:107], off
	s_nop 0
	v_mfma_f32_16x16x32_bf16 v[56:59], v[154:157], v[12:15], v[36:39]
	v_mov_b32_e32 v106, v244
	v_mov_b32_e32 v107, v245
	v_mov_b32_e32 v108, v246
	v_mov_b32_e32 v109, v247
	v_mov_b32_e32 v112, v186
	v_mov_b32_e32 v113, v187
	v_lshlrev_b32_e32 v73, 16, v112
	s_nop 5
	v_fma_f32 v56, v56, v106, v71
	v_mul_f32_e32 v56, v56, v73
	v_and_b32_e32 v73, 0xffff0000, v112
	v_fma_f32 v57, v57, v107, v71
	v_mul_f32_e32 v57, v57, v73
	v_lshlrev_b32_e32 v73, 16, v113
	v_fma_f32 v58, v58, v108, v71
	v_mul_f32_e32 v58, v58, v73
	v_and_b32_e32 v73, 0xffff0000, v113
	v_fma_f32 v59, v59, v109, v71
	v_mul_f32_e32 v59, v59, v73
	v_cvt_pk_bf16_f32 v56, v56, v57
	v_cvt_pk_bf16_f32 v57, v58, v59
	global_store_dwordx2 v[110:111], v[56:57], off offset:32
	s_nop 0
	s_waitcnt lgkmcnt(0)
	v_mfma_f32_16x16x32_bf16 v[48:51], v[176:179], v[12:15], v[0:3]
	v_mov_b32_e32 v56, v248
	v_mov_b32_e32 v57, v249
	v_mov_b32_e32 v58, v250
	v_mov_b32_e32 v59, v251
	v_mov_b32_e32 v106, v188
	v_mov_b32_e32 v107, v189
	v_fma_f32 v52, v52, v56, v71
	v_and_b32_e32 v56, 0xffff0000, v106
	v_fma_f32 v53, v53, v57, v71
	v_lshlrev_b32_e32 v73, 16, v106
	v_mul_f32_e32 v53, v53, v56
	v_lshlrev_b32_e32 v56, 16, v107
	v_fma_f32 v54, v54, v58, v71
	v_mul_f32_e32 v52, v52, v73
	v_mul_f32_e32 v54, v54, v56
	v_and_b32_e32 v56, 0xffff0000, v107
	v_fma_f32 v55, v55, v59, v71
	v_mul_f32_e32 v55, v55, v56
	v_cvt_pk_bf16_f32 v52, v52, v53
	v_cvt_pk_bf16_f32 v53, v54, v55
	global_store_dwordx2 v[110:111], v[52:53], off offset:64
	s_nop 0
	v_mfma_f32_16x16x32_bf16 v[44:47], v[150:153], v[16:19], v[28:31]
	v_mov_b32_e32 v52, v216
	v_mov_b32_e32 v53, v217
	v_mov_b32_e32 v54, v252
	v_mov_b32_e32 v55, v253
	v_mov_b32_e32 v56, v190
	v_mov_b32_e32 v57, v191
	v_fma_f32 v48, v48, v52, v71
	v_lshlrev_b32_e32 v58, 16, v56
	v_and_b32_e32 v52, 0xffff0000, v56
	v_fma_f32 v49, v49, v53, v71
	v_mul_f32_e32 v48, v48, v58
	v_mul_f32_e32 v49, v49, v52
	v_lshlrev_b32_e32 v52, 16, v57
	v_fma_f32 v50, v50, v54, v71
	v_mul_f32_e32 v50, v50, v52
	v_and_b32_e32 v52, 0xffff0000, v57
	v_fmac_f32_e32 v71, v51, v55
	v_cvt_pk_bf16_f32 v48, v48, v49
	v_mul_f32_e32 v51, v71, v52
	v_cvt_pk_bf16_f32 v49, v50, v51
	global_store_dwordx2 v[110:111], v[48:49], off offset:96
	v_add_u32_e32 v48, s33, v99
	v_ashrrev_i32_e32 v49, 31, v48
	v_lshlrev_b64 v[48:49], 13, v[48:49]
	v_lshl_add_u64 v[52:53], s[0:1], 0, v[48:49]
	v_lshl_add_u64 v[52:53], v[52:53], 0, v[76:77]
	v_mfma_f32_16x16x32_bf16 v[36:39], v[158:161], v[16:19], v[142:145]
	v_mov_b32_e32 v56, v235
	v_mov_b32_e32 v48, v240
	v_mov_b32_e32 v49, v241
	v_mov_b32_e32 v50, v242
	v_mov_b32_e32 v51, v243
	v_mov_b32_e32 v54, v192
	v_mov_b32_e32 v55, v193
	v_fma_f32 v44, v44, v48, v56
	v_and_b32_e32 v48, 0xffff0000, v54
	v_fma_f32 v45, v45, v49, v56
	v_lshlrev_b32_e32 v57, 16, v54
	v_mul_f32_e32 v45, v45, v48
	v_lshlrev_b32_e32 v48, 16, v55
	v_fma_f32 v46, v46, v50, v56
	v_mul_f32_e32 v44, v44, v57
	v_mul_f32_e32 v46, v46, v48
	v_and_b32_e32 v48, 0xffff0000, v55
	v_fma_f32 v47, v47, v51, v56
	v_mul_f32_e32 v47, v47, v48
	v_cvt_pk_bf16_f32 v44, v44, v45
	v_cvt_pk_bf16_f32 v45, v46, v47
	global_store_dwordx2 v[52:53], v[44:45], off
	s_nop 0
	v_mfma_f32_16x16x32_bf16 v[32:35], v[176:179], v[16:19], v[4:7]
	v_mov_b32_e32 v44, v244
	v_mov_b32_e32 v45, v245
	v_mov_b32_e32 v46, v246
	v_mov_b32_e32 v47, v247
	v_mov_b32_e32 v48, v194
	v_mov_b32_e32 v49, v195
	v_fma_f32 v40, v40, v44, v56
	v_and_b32_e32 v44, 0xffff0000, v48
	v_fma_f32 v41, v41, v45, v56
	v_lshlrev_b32_e32 v50, 16, v48
	v_mul_f32_e32 v41, v41, v44
	v_lshlrev_b32_e32 v44, 16, v49
	v_fma_f32 v42, v42, v46, v56
	v_mul_f32_e32 v40, v40, v50
	v_mul_f32_e32 v42, v42, v44
	v_and_b32_e32 v44, 0xffff0000, v49
	v_fma_f32 v43, v43, v47, v56
	v_mul_f32_e32 v43, v43, v44
	v_cvt_pk_bf16_f32 v40, v40, v41
	v_cvt_pk_bf16_f32 v41, v42, v43
	global_store_dwordx2 v[52:53], v[40:41], off offset:32
	s_nop 0
	v_mfma_f32_16x16x32_bf16 v[28:31], v[150:153], v[134:137], v[114:117]
	v_mov_b32_e32 v40, v248
	v_mov_b32_e32 v41, v249
	v_mov_b32_e32 v42, v250
	v_mov_b32_e32 v43, v251
	v_mov_b32_e32 v44, v196
	v_mov_b32_e32 v45, v197
	v_fma_f32 v36, v36, v40, v56
	v_and_b32_e32 v40, 0xffff0000, v44
	v_fma_f32 v37, v37, v41, v56
	v_lshlrev_b32_e32 v46, 16, v44
	v_mul_f32_e32 v37, v37, v40
	v_lshlrev_b32_e32 v40, 16, v45
	v_fma_f32 v38, v38, v42, v56
	v_mul_f32_e32 v36, v36, v46
	v_mul_f32_e32 v38, v38, v40
	v_and_b32_e32 v40, 0xffff0000, v45
	v_fma_f32 v39, v39, v43, v56
	v_mul_f32_e32 v39, v39, v40
	v_cvt_pk_bf16_f32 v36, v36, v37
	v_cvt_pk_bf16_f32 v37, v38, v39
	global_store_dwordx2 v[52:53], v[36:37], off offset:64
	s_nop 0
	v_mfma_f32_16x16x32_bf16 v[24:27], v[154:157], v[134:137], v[146:149]
	v_mov_b32_e32 v36, v216
	v_mov_b32_e32 v37, v217
	v_mov_b32_e32 v38, v252
	v_mov_b32_e32 v39, v253
	v_mov_b32_e32 v40, v198
	v_mov_b32_e32 v41, v199
	v_fma_f32 v32, v32, v36, v56
	v_lshlrev_b32_e32 v42, 16, v40
	v_and_b32_e32 v36, 0xffff0000, v40
	v_fma_f32 v33, v33, v37, v56
	v_mul_f32_e32 v32, v32, v42
	v_mul_f32_e32 v33, v33, v36
	v_lshlrev_b32_e32 v36, 16, v41
	v_fma_f32 v34, v34, v38, v56
	v_mul_f32_e32 v34, v34, v36
	v_and_b32_e32 v36, 0xffff0000, v41
	v_fmac_f32_e32 v56, v35, v39
	v_cvt_pk_bf16_f32 v32, v32, v33
	v_mul_f32_e32 v35, v56, v36
	v_cvt_pk_bf16_f32 v33, v34, v35
	global_store_dwordx2 v[52:53], v[32:33], off offset:96
	v_add_u32_e32 v32, s33, v100
	v_ashrrev_i32_e32 v33, 31, v32
	v_lshlrev_b64 v[32:33], 13, v[32:33]
	v_lshl_add_u64 v[36:37], s[0:1], 0, v[32:33]
	v_lshl_add_u64 v[36:37], v[36:37], 0, v[76:77]
	v_mfma_f32_16x16x32_bf16 v[16:19], v[176:179], v[134:137], v[8:11]
	v_mov_b32_e32 v40, v237
	v_mov_b32_e32 v32, v240
	v_mov_b32_e32 v33, v241
	v_mov_b32_e32 v34, v242
	v_mov_b32_e32 v35, v243
	v_mov_b32_e32 v38, v200
	v_mov_b32_e32 v39, v201
	v_fma_f32 v28, v28, v32, v40
	v_and_b32_e32 v32, 0xffff0000, v38
	v_fma_f32 v29, v29, v33, v40
	v_lshlrev_b32_e32 v41, 16, v38
	v_mul_f32_e32 v29, v29, v32
	v_lshlrev_b32_e32 v32, 16, v39
	v_fma_f32 v30, v30, v34, v40
	v_mul_f32_e32 v28, v28, v41
	v_mul_f32_e32 v30, v30, v32
	v_and_b32_e32 v32, 0xffff0000, v39
	v_fma_f32 v31, v31, v35, v40
	v_mul_f32_e32 v31, v31, v32
	v_cvt_pk_bf16_f32 v28, v28, v29
	v_cvt_pk_bf16_f32 v29, v30, v31
	global_store_dwordx2 v[36:37], v[28:29], off
	s_nop 0
	v_mfma_f32_16x16x32_bf16 v[12:15], v[150:153], v[138:141], v[118:121]
	v_mov_b32_e32 v28, v244
	v_mov_b32_e32 v29, v245
	v_mov_b32_e32 v30, v246
	v_mov_b32_e32 v31, v247
	v_mov_b32_e32 v32, v202
	v_mov_b32_e32 v33, v203
	v_fma_f32 v24, v24, v28, v40
	v_and_b32_e32 v28, 0xffff0000, v32
	v_fma_f32 v25, v25, v29, v40
	v_lshlrev_b32_e32 v34, 16, v32
	v_mul_f32_e32 v25, v25, v28
	v_lshlrev_b32_e32 v28, 16, v33
	v_fma_f32 v26, v26, v30, v40
	v_mul_f32_e32 v24, v24, v34
	v_mul_f32_e32 v26, v26, v28
	v_and_b32_e32 v28, 0xffff0000, v33
	v_fma_f32 v27, v27, v31, v40
	v_mul_f32_e32 v27, v27, v28
	v_cvt_pk_bf16_f32 v24, v24, v25
	v_cvt_pk_bf16_f32 v25, v26, v27
	global_store_dwordx2 v[36:37], v[24:25], off offset:32
	s_nop 0
	v_mfma_f32_16x16x32_bf16 v[8:11], v[154:157], v[138:141], v[126:129]
	v_mov_b32_e32 v24, v248
	v_mov_b32_e32 v25, v249
	v_mov_b32_e32 v26, v250
	v_mov_b32_e32 v27, v251
	v_mov_b32_e32 v28, v204
	v_mov_b32_e32 v29, v205
	v_fma_f32 v20, v20, v24, v40
	v_and_b32_e32 v24, 0xffff0000, v28
	v_fma_f32 v21, v21, v25, v40
	v_lshlrev_b32_e32 v30, 16, v28
	v_mul_f32_e32 v21, v21, v24
	v_lshlrev_b32_e32 v24, 16, v29
	v_fma_f32 v22, v22, v26, v40
	v_mul_f32_e32 v20, v20, v30
	v_mul_f32_e32 v22, v22, v24
	v_and_b32_e32 v24, 0xffff0000, v29
	v_fma_f32 v23, v23, v27, v40
	v_mul_f32_e32 v23, v23, v24
	v_cvt_pk_bf16_f32 v20, v20, v21
	v_cvt_pk_bf16_f32 v21, v22, v23
	global_store_dwordx2 v[36:37], v[20:21], off offset:64
	s_nop 0
	v_mfma_f32_16x16x32_bf16 v[4:7], v[158:161], v[138:141], v[130:133]
	v_mov_b32_e32 v20, v216
	v_mov_b32_e32 v21, v217
	v_mov_b32_e32 v22, v252
	v_mov_b32_e32 v23, v253
	v_mov_b32_e32 v24, v206
	v_mov_b32_e32 v25, v207
	v_fma_f32 v16, v16, v20, v40
	v_lshlrev_b32_e32 v26, 16, v24
	v_and_b32_e32 v20, 0xffff0000, v24
	v_fma_f32 v17, v17, v21, v40
	v_mul_f32_e32 v16, v16, v26
	v_mul_f32_e32 v17, v17, v20
	v_lshlrev_b32_e32 v20, 16, v25
	v_fma_f32 v18, v18, v22, v40
	v_mul_f32_e32 v18, v18, v20
	v_and_b32_e32 v20, 0xffff0000, v25
	v_fmac_f32_e32 v40, v19, v23
	v_cvt_pk_bf16_f32 v16, v16, v17
	v_mul_f32_e32 v19, v40, v20
	v_cvt_pk_bf16_f32 v17, v18, v19
	global_store_dwordx2 v[36:37], v[16:17], off offset:96
	v_add_u32_e32 v16, s33, v101
	v_ashrrev_i32_e32 v17, 31, v16
	v_lshlrev_b64 v[16:17], 13, v[16:17]
	v_lshl_add_u64 v[20:21], s[0:1], 0, v[16:17]
	v_lshl_add_u64 v[20:21], v[20:21], 0, v[76:77]
	v_mfma_f32_16x16x32_bf16 v[0:3], v[176:179], v[138:141], v[122:125]
	v_mov_b32_e32 v22, v228
	v_mov_b32_e32 v16, v240
	v_mov_b32_e32 v17, v241
	v_mov_b32_e32 v18, v242
	v_mov_b32_e32 v19, v243
	v_mov_b32_e32 v24, v208
	v_mov_b32_e32 v25, v209
	v_fma_f32 v12, v12, v16, v22
	v_and_b32_e32 v16, 0xffff0000, v24
	v_fma_f32 v13, v13, v17, v22
	v_lshlrev_b32_e32 v23, 16, v24
	v_mul_f32_e32 v13, v13, v16
	v_lshlrev_b32_e32 v16, 16, v25
	v_fma_f32 v14, v14, v18, v22
	v_mul_f32_e32 v12, v12, v23
	v_mul_f32_e32 v14, v14, v16
	v_and_b32_e32 v16, 0xffff0000, v25
	v_fma_f32 v15, v15, v19, v22
	v_mul_f32_e32 v15, v15, v16
	v_cvt_pk_bf16_f32 v12, v12, v13
	v_cvt_pk_bf16_f32 v13, v14, v15
	global_store_dwordx2 v[20:21], v[12:13], off
	s_nop 0
	v_mov_b32_e32 v12, v244
	v_mov_b32_e32 v13, v245
	v_mov_b32_e32 v14, v246
	v_mov_b32_e32 v15, v247
	v_mov_b32_e32 v16, v210
	v_mov_b32_e32 v17, v211
	v_fma_f32 v8, v8, v12, v22
	v_and_b32_e32 v12, 0xffff0000, v16
	v_fma_f32 v9, v9, v13, v22
	v_lshlrev_b32_e32 v18, 16, v16
	v_mul_f32_e32 v9, v9, v12
	v_lshlrev_b32_e32 v12, 16, v17
	v_fma_f32 v10, v10, v14, v22
	v_mul_f32_e32 v8, v8, v18
	v_mul_f32_e32 v10, v10, v12
	v_and_b32_e32 v12, 0xffff0000, v17
	v_fma_f32 v11, v11, v15, v22
	v_mul_f32_e32 v11, v11, v12
	v_cvt_pk_bf16_f32 v8, v8, v9
	v_cvt_pk_bf16_f32 v9, v10, v11
	global_store_dwordx2 v[20:21], v[8:9], off offset:32
	s_nop 0
	v_mov_b32_e32 v8, v248
	v_mov_b32_e32 v9, v249
	v_mov_b32_e32 v10, v250
	v_mov_b32_e32 v11, v251
	v_mov_b32_e32 v12, v212
	v_mov_b32_e32 v13, v213
	v_fma_f32 v4, v4, v8, v22
	v_and_b32_e32 v8, 0xffff0000, v12
	v_fma_f32 v5, v5, v9, v22
	v_lshlrev_b32_e32 v14, 16, v12
	v_mul_f32_e32 v5, v5, v8
	v_lshlrev_b32_e32 v8, 16, v13
	v_fma_f32 v6, v6, v10, v22
	v_mul_f32_e32 v4, v4, v14
	v_mul_f32_e32 v6, v6, v8
	v_and_b32_e32 v8, 0xffff0000, v13
	v_fma_f32 v7, v7, v11, v22
	v_mul_f32_e32 v7, v7, v8
	v_cvt_pk_bf16_f32 v4, v4, v5
	v_cvt_pk_bf16_f32 v5, v6, v7
	global_store_dwordx2 v[20:21], v[4:5], off offset:64
	s_nop 0
	v_mov_b32_e32 v4, v216
	v_mov_b32_e32 v5, v217
	v_mov_b32_e32 v6, v252
	v_mov_b32_e32 v7, v253
	v_mov_b32_e32 v8, v214
	v_mov_b32_e32 v9, v215
	v_fma_f32 v0, v0, v4, v22
	v_and_b32_e32 v4, 0xffff0000, v8
	v_fma_f32 v1, v1, v5, v22
	v_lshlrev_b32_e32 v10, 16, v8
	v_mul_f32_e32 v1, v1, v4
	v_lshlrev_b32_e32 v4, 16, v9
	v_fma_f32 v2, v2, v6, v22
	v_mul_f32_e32 v0, v0, v10
	v_mul_f32_e32 v2, v2, v4
	v_and_b32_e32 v4, 0xffff0000, v9
	v_fmac_f32_e32 v22, v3, v7
	v_mul_f32_e32 v3, v22, v4
	v_cvt_pk_bf16_f32 v0, v0, v1
	v_cvt_pk_bf16_f32 v1, v2, v3
	global_store_dwordx2 v[20:21], v[0:1], off offset:96
	s_barrier
	s_cbranch_scc1 .LBB0_688
	v_readlane_b32 s69, v255, 16
	v_readlane_b32 s76, v255, 15
	v_readlane_b32 s79, v255, 14
